# gate int8 epilogue: bias, int8 row scales, matrix step and row stats all prefetched by LDS-DMA in the last K-iteration (SST slot + RED area), read with ds_read; one barrier before the SST write
# baseline (speedup 1.0000x reference)
.LBB0_1026:
	s_add_i32 s28, s10, 2
	s_cmp_eq_u32 s71, s10
	s_cselect_b32 s46, s4, s74
	s_cselect_b32 s47, s5, s75
	s_cselect_b32 s44, s42, s72
	s_cselect_b32 s45, s43, s73
	s_cbranch_scc0 .Lg0_nopf
	v_mbcnt_lo_u32_b32 v250, -1, 0
	v_mbcnt_hi_u32_b32 v250, -1, v250
	v_lshlrev_b32_e32 v251, 4, v250
	s_lshl_b32 s76, s67, 13
	s_add_u32 s76, s20, s76
	s_addc_u32 s77, s21, 0
	v_add_u32_e32 v252, s49, v251
	s_add_i32 m0, s49, 0x24f80
	s_nop 0
	global_load_lds_dwordx4 v252, s[76:77]
	s_lshl_b32 s76, s68, 12
	s_lshl_b32 s77, s70, 10
	s_add_i32 s76, s76, s77
	s_add_u32 s76, s57, s76
	s_addc_u32 s77, s60, 0
	s_mov_b32 m0, 0x26f80
	s_nop 0
	global_load_lds_dwordx4 v251, s[76:77]
	s_lshl_b32 s76, s67, 10
	s_add_u32 s76, s22, s76
	s_addc_u32 s77, s23, 0
	s_mov_b32 m0, 0x27380
	s_nop 0
	global_load_lds_dwordx4 v251, s[76:77]
	s_ashr_i32 s76, s68, 1
	s_lshl_b32 s76, s76, 2
	s_add_u32 s76, s12, s76
	s_addc_u32 s77, s61, 0
	v_mov_b32_e32 v253, 0
	s_mov_b32 m0, 0x27780
	s_nop 0
	global_load_lds_dword v253, s[76:77] sc1
.Lg0_nopf:
	s_add_u32 s10, s46, 0x80
	s_addc_u32 s11, s47, 0
	s_add_i32 s29, 0, 0x10000
	s_add_i32 s78, 0, 0x14000
	v_add_u32_e32 v142, s29, v179
	v_add_u32_e32 v160, s78, v179
	ds_read_b128 v[130:133], v142
	ds_read_b128 v[134:137], v142 offset:1024
	ds_read_b128 v[138:141], v142 offset:2048
	ds_read_b128 v[142:145], v142 offset:3072
	ds_read_b128 v[146:149], v160
	ds_read_b128 v[150:153], v160 offset:1024
	ds_read_b128 v[154:157], v160 offset:2048
	ds_read_b128 v[160:163], v160 offset:3072
	s_add_u32 s76, s74, 0x7ff80
	v_add_u32_e32 v200, 0, v178
	s_addc_u32 s77, s75, 0
	ds_read_b128 v[164:167], v200
	ds_read_b128 v[168:171], v200 offset:1024
	ds_read_b128 v[172:175], v200 offset:2048
	ds_read_b128 v[180:183], v200 offset:3072
	ds_read_b128 v[184:187], v200 offset:4096
	ds_read_b128 v[188:191], v200 offset:5120
	ds_read_b128 v[192:195], v200 offset:6144
	ds_read_b128 v[196:199], v200 offset:7168
	s_add_i32 m0, s49, 0xc000
	v_lshl_add_u64 v[176:177], s[76:77], 0, v[158:159]
	s_add_u32 s76, s76, 0x40000
	s_addc_u32 s77, s77, 0
	global_load_lds_dwordx4 v[176:177], off
	s_add_i32 m0, s49, 0xe000
	v_lshl_add_u64 v[176:177], s[76:77], 0, v[158:159]
	global_load_lds_dwordx4 v[176:177], off
	s_waitcnt vmcnt(8)
	s_waitcnt lgkmcnt(0)
	s_barrier
	s_setprio 1
	s_waitcnt lgkmcnt(0)
	v_mfma_i32_16x16x64_i8 v[126:129], v[130:133], v[164:167], v[126:129]
	v_mfma_i32_16x16x64_i8 v[122:125], v[138:141], v[164:167], v[122:125]
	v_mfma_i32_16x16x64_i8 v[118:121], v[130:133], v[172:175], v[118:121]
	v_mfma_i32_16x16x64_i8 v[114:117], v[138:141], v[172:175], v[114:117]
	v_mfma_i32_16x16x64_i8 v[102:105], v[130:133], v[184:187], v[102:105]
	v_mfma_i32_16x16x64_i8 v[98:101], v[138:141], v[184:187], v[98:101]
	v_mfma_i32_16x16x64_i8 v[86:89], v[130:133], v[192:195], v[86:89]
	v_mfma_i32_16x16x64_i8 v[82:85], v[138:141], v[192:195], v[82:85]
	v_mfma_i32_16x16x64_i8 v[126:129], v[134:137], v[168:171], v[126:129]
	v_mfma_i32_16x16x64_i8 v[122:125], v[142:145], v[168:171], v[122:125]
	v_mfma_i32_16x16x64_i8 v[118:121], v[134:137], v[180:183], v[118:121]
	v_mfma_i32_16x16x64_i8 v[114:117], v[142:145], v[180:183], v[114:117]
	v_mfma_i32_16x16x64_i8 v[102:105], v[134:137], v[188:191], v[102:105]
	v_mfma_i32_16x16x64_i8 v[98:101], v[142:145], v[188:191], v[98:101]
	v_mfma_i32_16x16x64_i8 v[86:89], v[134:137], v[196:199], v[86:89]
	v_mfma_i32_16x16x64_i8 v[82:85], v[142:145], v[196:199], v[82:85]
	s_setprio 0
	s_setprio 1
	v_mfma_i32_16x16x64_i8 v[110:113], v[146:149], v[164:167], v[110:113]
	v_mfma_i32_16x16x64_i8 v[106:109], v[154:157], v[164:167], v[106:109]
	v_mfma_i32_16x16x64_i8 v[94:97], v[146:149], v[172:175], v[94:97]
	v_mfma_i32_16x16x64_i8 v[90:93], v[154:157], v[172:175], v[90:93]
	v_mfma_i32_16x16x64_i8 v[78:81], v[146:149], v[184:187], v[78:81]
	v_mfma_i32_16x16x64_i8 v[74:77], v[154:157], v[184:187], v[74:77]
	v_mfma_i32_16x16x64_i8 v[70:73], v[146:149], v[192:195], v[70:73]
	v_mfma_i32_16x16x64_i8 v[66:69], v[154:157], v[192:195], v[66:69]
	v_mfma_i32_16x16x64_i8 v[110:113], v[150:153], v[168:171], v[110:113]
	v_mfma_i32_16x16x64_i8 v[106:109], v[160:163], v[168:171], v[106:109]
	v_mfma_i32_16x16x64_i8 v[94:97], v[150:153], v[180:183], v[94:97]
	v_mfma_i32_16x16x64_i8 v[90:93], v[160:163], v[180:183], v[90:93]
	v_mfma_i32_16x16x64_i8 v[78:81], v[150:153], v[188:191], v[78:81]
	v_mfma_i32_16x16x64_i8 v[74:77], v[160:163], v[188:191], v[74:77]
	v_mfma_i32_16x16x64_i8 v[70:73], v[150:153], v[196:199], v[70:73]
	v_mfma_i32_16x16x64_i8 v[66:69], v[160:163], v[196:199], v[66:69]
	s_setprio 0
	s_barrier
	s_mov_b64 s[76:77], s[44:45]
	ds_read_b128 v[164:167], v200 offset:16384
	ds_read_b128 v[168:171], v200 offset:17408
	ds_read_b128 v[172:175], v200 offset:18432
	ds_read_b128 v[180:183], v200 offset:19456
	ds_read_b128 v[184:187], v200 offset:20480
	ds_read_b128 v[188:191], v200 offset:21504
	ds_read_b128 v[192:195], v200 offset:22528
	ds_read_b128 v[196:199], v200 offset:23552
	s_add_i32 s29, s29, s48
	v_lshl_add_u64 v[176:177], s[76:77], 0, v[202:203]
	s_add_u32 s76, s76, 0x30000
	s_mov_b32 m0, s29
	s_addc_u32 s77, s77, 0
	global_load_lds_dwordx4 v[176:177], off
	s_add_i32 m0, s29, 0x2000
	v_lshl_add_u64 v[176:177], s[76:77], 0, v[202:203]
	s_add_u32 s76, s44, 0x60000
	s_addc_u32 s77, s45, 0
	global_load_lds_dwordx4 v[176:177], off
	s_add_i32 s29, s78, s48
	v_lshl_add_u64 v[176:177], s[76:77], 0, v[202:203]
	s_add_u32 s76, s76, 0x30000
	s_mov_b32 m0, s29
	s_addc_u32 s77, s77, 0
	global_load_lds_dwordx4 v[176:177], off
	s_add_i32 m0, s29, 0x2000
	v_lshl_add_u64 v[176:177], s[76:77], 0, v[202:203]
	s_mov_b64 s[76:77], s[46:47]
	global_load_lds_dwordx4 v[176:177], off
	s_mov_b32 m0, s49
	v_lshl_add_u64 v[176:177], s[76:77], 0, v[158:159]
	s_add_u32 s76, s76, 0x40000
	s_addc_u32 s77, s77, 0
	global_load_lds_dwordx4 v[176:177], off
	s_mov_b32 m0, s50
	v_lshl_add_u64 v[176:177], s[76:77], 0, v[158:159]
	global_load_lds_dwordx4 v[176:177], off
	s_waitcnt vmcnt(8)
	s_waitcnt lgkmcnt(0)
	s_barrier
	s_setprio 1
	s_waitcnt lgkmcnt(0)
	v_mfma_i32_16x16x64_i8 v[62:65], v[130:133], v[164:167], v[62:65]
	v_mfma_i32_16x16x64_i8 v[58:61], v[138:141], v[164:167], v[58:61]
	v_mfma_i32_16x16x64_i8 v[54:57], v[130:133], v[172:175], v[54:57]
	v_mfma_i32_16x16x64_i8 v[50:53], v[138:141], v[172:175], v[50:53]
	v_mfma_i32_16x16x64_i8 v[38:41], v[130:133], v[184:187], v[38:41]
	v_mfma_i32_16x16x64_i8 v[34:37], v[138:141], v[184:187], v[34:37]
	v_mfma_i32_16x16x64_i8 v[14:17], v[130:133], v[192:195], v[14:17]
	v_mfma_i32_16x16x64_i8 v[10:13], v[138:141], v[192:195], v[10:13]
	v_mfma_i32_16x16x64_i8 v[62:65], v[134:137], v[168:171], v[62:65]
	v_mfma_i32_16x16x64_i8 v[58:61], v[142:145], v[168:171], v[58:61]
	v_mfma_i32_16x16x64_i8 v[54:57], v[134:137], v[180:183], v[54:57]
	v_mfma_i32_16x16x64_i8 v[50:53], v[142:145], v[180:183], v[50:53]
	v_mfma_i32_16x16x64_i8 v[38:41], v[134:137], v[188:191], v[38:41]
	v_mfma_i32_16x16x64_i8 v[34:37], v[142:145], v[188:191], v[34:37]
	v_mfma_i32_16x16x64_i8 v[14:17], v[134:137], v[196:199], v[14:17]
	v_mfma_i32_16x16x64_i8 v[10:13], v[142:145], v[196:199], v[10:13]
	s_setprio 0
	s_setprio 1
	v_mfma_i32_16x16x64_i8 v[46:49], v[146:149], v[164:167], v[46:49]
	v_mfma_i32_16x16x64_i8 v[42:45], v[154:157], v[164:167], v[42:45]
	v_mfma_i32_16x16x64_i8 v[30:33], v[146:149], v[172:175], v[30:33]
	v_mfma_i32_16x16x64_i8 v[26:29], v[154:157], v[172:175], v[26:29]
	v_mfma_i32_16x16x64_i8 v[22:25], v[146:149], v[184:187], v[22:25]
	v_mfma_i32_16x16x64_i8 v[18:21], v[154:157], v[184:187], v[18:21]
	v_mfma_i32_16x16x64_i8 v[6:9], v[146:149], v[192:195], v[6:9]
	v_mfma_i32_16x16x64_i8 v[2:5], v[154:157], v[192:195], v[2:5]
	v_mfma_i32_16x16x64_i8 v[46:49], v[150:153], v[168:171], v[46:49]
	v_mfma_i32_16x16x64_i8 v[42:45], v[160:163], v[168:171], v[42:45]
	v_mfma_i32_16x16x64_i8 v[30:33], v[150:153], v[180:183], v[30:33]
	v_mfma_i32_16x16x64_i8 v[26:29], v[160:163], v[180:183], v[26:29]
	v_mfma_i32_16x16x64_i8 v[22:25], v[150:153], v[188:191], v[22:25]
	v_mfma_i32_16x16x64_i8 v[18:21], v[160:163], v[188:191], v[18:21]
	v_mfma_i32_16x16x64_i8 v[6:9], v[150:153], v[196:199], v[6:9]
	v_mfma_i32_16x16x64_i8 v[2:5], v[160:163], v[196:199], v[2:5]
	s_setprio 0
	s_barrier
	s_add_i32 s29, 0, 0x18000
	s_add_i32 s76, 0, 0x1c000
	v_add_u32_e32 v142, s29, v179
	v_add_u32_e32 v160, s76, v179
	ds_read_b128 v[130:133], v142
	ds_read_b128 v[134:137], v142 offset:1024
	ds_read_b128 v[138:141], v142 offset:2048
	ds_read_b128 v[142:145], v142 offset:3072
	ds_read_b128 v[146:149], v160
	ds_read_b128 v[150:153], v160 offset:1024
	ds_read_b128 v[154:157], v160 offset:2048
	ds_read_b128 v[160:163], v160 offset:3072
	s_add_u32 s46, s46, 0x80000
	s_addc_u32 s47, s47, 0
	ds_read_b128 v[164:167], v200 offset:32768
	ds_read_b128 v[168:171], v200 offset:33792
	ds_read_b128 v[172:175], v200 offset:34816
	ds_read_b128 v[180:183], v200 offset:35840
	ds_read_b128 v[184:187], v200 offset:36864
	ds_read_b128 v[188:191], v200 offset:37888
	ds_read_b128 v[192:195], v200 offset:38912
	ds_read_b128 v[196:199], v200 offset:39936
	s_mov_b32 m0, s51
	v_lshl_add_u64 v[176:177], s[46:47], 0, v[158:159]
	s_add_u32 s46, s46, 0x40000
	s_addc_u32 s47, s47, 0
	global_load_lds_dwordx4 v[176:177], off
	s_mov_b32 m0, s52
	v_lshl_add_u64 v[176:177], s[46:47], 0, v[158:159]
	global_load_lds_dwordx4 v[176:177], off
	s_waitcnt vmcnt(8)
	s_waitcnt lgkmcnt(0)
	s_barrier
	s_setprio 1
	s_waitcnt lgkmcnt(0)
	v_mfma_i32_16x16x64_i8 v[126:129], v[130:133], v[164:167], v[126:129]
	v_mfma_i32_16x16x64_i8 v[122:125], v[138:141], v[164:167], v[122:125]
	v_mfma_i32_16x16x64_i8 v[118:121], v[130:133], v[172:175], v[118:121]
	v_mfma_i32_16x16x64_i8 v[114:117], v[138:141], v[172:175], v[114:117]
	v_mfma_i32_16x16x64_i8 v[102:105], v[130:133], v[184:187], v[102:105]
	v_mfma_i32_16x16x64_i8 v[98:101], v[138:141], v[184:187], v[98:101]
	v_mfma_i32_16x16x64_i8 v[86:89], v[130:133], v[192:195], v[86:89]
	v_mfma_i32_16x16x64_i8 v[82:85], v[138:141], v[192:195], v[82:85]
	v_mfma_i32_16x16x64_i8 v[126:129], v[134:137], v[168:171], v[126:129]
	v_mfma_i32_16x16x64_i8 v[122:125], v[142:145], v[168:171], v[122:125]
	v_mfma_i32_16x16x64_i8 v[118:121], v[134:137], v[180:183], v[118:121]
	v_mfma_i32_16x16x64_i8 v[114:117], v[142:145], v[180:183], v[114:117]
	v_mfma_i32_16x16x64_i8 v[102:105], v[134:137], v[188:191], v[102:105]
	v_mfma_i32_16x16x64_i8 v[98:101], v[142:145], v[188:191], v[98:101]
	v_mfma_i32_16x16x64_i8 v[86:89], v[134:137], v[196:199], v[86:89]
	v_mfma_i32_16x16x64_i8 v[82:85], v[142:145], v[196:199], v[82:85]
	s_setprio 0
	s_setprio 1
	v_mfma_i32_16x16x64_i8 v[110:113], v[146:149], v[164:167], v[110:113]
	v_mfma_i32_16x16x64_i8 v[106:109], v[154:157], v[164:167], v[106:109]
	v_mfma_i32_16x16x64_i8 v[94:97], v[146:149], v[172:175], v[94:97]
	v_mfma_i32_16x16x64_i8 v[90:93], v[154:157], v[172:175], v[90:93]
	v_mfma_i32_16x16x64_i8 v[78:81], v[146:149], v[184:187], v[78:81]
	v_mfma_i32_16x16x64_i8 v[74:77], v[154:157], v[184:187], v[74:77]
	v_mfma_i32_16x16x64_i8 v[70:73], v[146:149], v[192:195], v[70:73]
	v_mfma_i32_16x16x64_i8 v[66:69], v[154:157], v[192:195], v[66:69]
	v_mfma_i32_16x16x64_i8 v[110:113], v[150:153], v[168:171], v[110:113]
	v_mfma_i32_16x16x64_i8 v[106:109], v[160:163], v[168:171], v[106:109]
	v_mfma_i32_16x16x64_i8 v[94:97], v[150:153], v[180:183], v[94:97]
	v_mfma_i32_16x16x64_i8 v[90:93], v[160:163], v[180:183], v[90:93]
	v_mfma_i32_16x16x64_i8 v[78:81], v[150:153], v[188:191], v[78:81]
	v_mfma_i32_16x16x64_i8 v[74:77], v[160:163], v[188:191], v[74:77]
	v_mfma_i32_16x16x64_i8 v[70:73], v[150:153], v[196:199], v[70:73]
	v_mfma_i32_16x16x64_i8 v[66:69], v[160:163], v[196:199], v[66:69]
	s_setprio 0
	s_barrier
	s_add_u32 s46, s44, 0x80
	s_addc_u32 s47, s45, 0
	ds_read_b128 v[164:167], v200 offset:49152
	ds_read_b128 v[168:171], v200 offset:50176
	ds_read_b128 v[172:175], v200 offset:51200
	ds_read_b128 v[180:183], v200 offset:52224
	ds_read_b128 v[184:187], v200 offset:53248
	ds_read_b128 v[188:191], v200 offset:54272
	ds_read_b128 v[192:195], v200 offset:55296
	ds_read_b128 v[196:199], v200 offset:56320
	s_add_i32 s29, s29, s48
	v_lshl_add_u64 v[176:177], s[46:47], 0, v[202:203]
	s_mov_b32 m0, s29
	s_add_u32 s46, s46, 0x30000
	global_load_lds_dwordx4 v[176:177], off
	s_addc_u32 s47, s47, 0
	s_add_i32 m0, s29, 0x2000
	s_add_u32 s44, s44, 0x60080
	s_addc_u32 s45, s45, 0
	v_lshl_add_u64 v[176:177], s[46:47], 0, v[202:203]
	global_load_lds_dwordx4 v[176:177], off
	s_add_i32 s29, s76, s48
	v_lshl_add_u64 v[176:177], s[44:45], 0, v[202:203]
	s_add_u32 s44, s44, 0x30000
	s_mov_b32 m0, s29
	s_addc_u32 s45, s45, 0
	global_load_lds_dwordx4 v[176:177], off
	s_add_i32 m0, s29, 0x2000
	v_lshl_add_u64 v[176:177], s[44:45], 0, v[202:203]
	global_load_lds_dwordx4 v[176:177], off
	s_mov_b32 m0, s53
	v_lshl_add_u64 v[176:177], s[10:11], 0, v[158:159]
	s_add_u32 s10, s10, 0x40000
	s_addc_u32 s11, s11, 0
	global_load_lds_dwordx4 v[176:177], off
	s_mov_b32 m0, s54
	v_lshl_add_u64 v[176:177], s[10:11], 0, v[158:159]
	global_load_lds_dwordx4 v[176:177], off
	s_waitcnt vmcnt(8)
	s_waitcnt lgkmcnt(0)
	s_barrier
	s_setprio 1
	s_waitcnt lgkmcnt(0)
	v_mfma_i32_16x16x64_i8 v[62:65], v[130:133], v[164:167], v[62:65]
	v_mfma_i32_16x16x64_i8 v[58:61], v[138:141], v[164:167], v[58:61]
	v_mfma_i32_16x16x64_i8 v[54:57], v[130:133], v[172:175], v[54:57]
	v_mfma_i32_16x16x64_i8 v[50:53], v[138:141], v[172:175], v[50:53]
	v_mfma_i32_16x16x64_i8 v[38:41], v[130:133], v[184:187], v[38:41]
	v_mfma_i32_16x16x64_i8 v[34:37], v[138:141], v[184:187], v[34:37]
	v_mfma_i32_16x16x64_i8 v[14:17], v[130:133], v[192:195], v[14:17]
	v_mfma_i32_16x16x64_i8 v[10:13], v[138:141], v[192:195], v[10:13]
	v_mfma_i32_16x16x64_i8 v[62:65], v[134:137], v[168:171], v[62:65]
	v_mfma_i32_16x16x64_i8 v[58:61], v[142:145], v[168:171], v[58:61]
	v_mfma_i32_16x16x64_i8 v[54:57], v[134:137], v[180:183], v[54:57]
	v_mfma_i32_16x16x64_i8 v[50:53], v[142:145], v[180:183], v[50:53]
	v_mfma_i32_16x16x64_i8 v[38:41], v[134:137], v[188:191], v[38:41]
	v_mfma_i32_16x16x64_i8 v[34:37], v[142:145], v[188:191], v[34:37]
	v_mfma_i32_16x16x64_i8 v[14:17], v[134:137], v[196:199], v[14:17]
	v_mfma_i32_16x16x64_i8 v[10:13], v[142:145], v[196:199], v[10:13]
	s_setprio 0
	s_setprio 1
	v_mfma_i32_16x16x64_i8 v[46:49], v[146:149], v[164:167], v[46:49]
	v_mfma_i32_16x16x64_i8 v[42:45], v[154:157], v[164:167], v[42:45]
	v_mfma_i32_16x16x64_i8 v[30:33], v[146:149], v[172:175], v[30:33]
	v_mfma_i32_16x16x64_i8 v[26:29], v[154:157], v[172:175], v[26:29]
	v_mfma_i32_16x16x64_i8 v[22:25], v[146:149], v[184:187], v[22:25]
	v_mfma_i32_16x16x64_i8 v[18:21], v[154:157], v[184:187], v[18:21]
	v_mfma_i32_16x16x64_i8 v[6:9], v[146:149], v[192:195], v[6:9]
	v_mfma_i32_16x16x64_i8 v[2:5], v[154:157], v[192:195], v[2:5]
	v_mfma_i32_16x16x64_i8 v[46:49], v[150:153], v[168:171], v[46:49]
	v_mfma_i32_16x16x64_i8 v[42:45], v[160:163], v[168:171], v[42:45]
	v_mfma_i32_16x16x64_i8 v[30:33], v[150:153], v[180:183], v[30:33]
	v_mfma_i32_16x16x64_i8 v[26:29], v[160:163], v[180:183], v[26:29]
	v_mfma_i32_16x16x64_i8 v[22:25], v[150:153], v[188:191], v[22:25]
	v_mfma_i32_16x16x64_i8 v[18:21], v[160:163], v[188:191], v[18:21]
	v_mfma_i32_16x16x64_i8 v[6:9], v[150:153], v[196:199], v[6:9]
	v_mfma_i32_16x16x64_i8 v[2:5], v[160:163], v[196:199], v[2:5]
	s_setprio 0
	s_barrier
	s_add_u32 s74, s74, 0x100
	s_addc_u32 s75, s75, 0
	s_add_u32 s72, s72, 0x100
	s_addc_u32 s73, s73, 0
	s_cmp_ge_i32 s28, s69
	s_mov_b32 s10, s28
	s_cbranch_scc0 .LBB0_1026
	s_and_b64 vcc, exec, s[18:19]
	s_cbranch_vccz .LBB0_1029
	s_barrier
.LBB0_1029:
	v_mov_b32_e32 v156, v0
	v_lshrrev_b32_e32 v246, 1, v156
	v_and_or_b32 v246, v246, 24, s63
	v_lshlrev_b32_e32 v246, 2, v246
	v_add_u32_e32 v246, 0x26f80, v246
	v_and_b32_e32 v236, 15, v156
	v_or_b32_e32 v236, s62, v236
	v_lshlrev_b32_e32 v224, 5, v236
	v_add_u32_e32 v224, 0x24f80, v224
	v_lshlrev_b32_e32 v236, 2, v236
	v_add_u32_e32 v236, 0x27380, v236
	v_mov_b32_e32 v254, 0x27780
	s_lshl_b32 s10, s68, 10
	s_lshl_b32 s5, s70, 8
	v_lshrrev_b32_e32 v130, 1, v156
	s_ashr_i32 s11, s10, 31
	s_ashr_i32 s4, s68, 1
	v_and_or_b32 v130, v130, 24, s5
	s_lshl_b64 s[10:11], s[10:11], 2
	v_or_b32_e32 v130, s63, v130
	s_add_u32 s10, s57, s10
	s_addc_u32 s11, s60, s11
	v_ashrrev_i32_e32 v131, 31, v130
	v_lshl_add_u64 v[138:139], v[130:131], 2, s[10:11]
	ds_read_b128 v[130:133], v246 offset:16
	ds_read_b128 v[134:137], v246
	ds_read_b128 v[160:163], v246 offset:528
	ds_read_b128 v[138:141], v246 offset:512
	v_and_b32_e32 v152, 15, v156
	s_lshl_b32 s10, s67, 8
	v_or_b32_e32 v142, s62, v152
	v_add_u32_e32 v142, s10, v142
	v_ashrrev_i32_e32 v143, 31, v142
	s_ashr_i32 s5, s4, 31
	v_lshl_add_u64 v[144:145], v[142:143], 2, s[22:23]
	v_add_u32_e32 v146, 0x80, v142
	v_add_u32_e32 v148, 0x90, v142
	v_add_u32_e32 v150, 0xa0, v142
	v_add_u32_e32 v142, 0xb0, v142
	s_lshl_b64 s[4:5], s[4:5], 2
	v_ashrrev_i32_e32 v143, 31, v142
	s_add_u32 s4, s12, s4
	v_ashrrev_i32_e32 v147, 31, v146
	v_ashrrev_i32_e32 v149, 31, v148
	v_ashrrev_i32_e32 v151, 31, v150
	v_lshl_add_u64 v[142:143], v[142:143], 2, s[22:23]
	s_addc_u32 s5, s61, s5
	s_add_i32 s10, s10, s62
	v_lshl_add_u64 v[146:147], v[146:147], 2, s[22:23]
	v_lshl_add_u64 v[148:149], v[148:149], 2, s[22:23]
	v_lshl_add_u64 v[150:151], v[150:151], 2, s[22:23]
	ds_read_b32 v157, v236
	ds_read_b32 v205, v236 offset:64
	ds_read_b32 v207, v236 offset:128
	ds_read_b32 v242, v236 offset:192
	ds_read_b32 v243, v236 offset:512
	ds_read_b32 v244, v236 offset:576
	ds_read_b32 v245, v236 offset:640
	ds_read_b32 v155, v236 offset:704
	v_or_b32_e32 v142, s10, v152
	v_ashrrev_i32_e32 v143, 31, v142
	v_lshlrev_b64 v[144:145], 5, v[142:143]
	v_lshl_add_u64 v[176:177], s[20:21], 0, v[144:145]
	ds_read_b32 v154, v254
	ds_read_b128 v[164:167], v224
	ds_read_b128 v[168:171], v224 offset:16
	v_or_b32_e32 v144, 16, v142
	v_ashrrev_i32_e32 v145, 31, v144
	v_lshlrev_b64 v[144:145], 5, v[144:145]
	v_lshl_add_u64 v[144:145], s[20:21], 0, v[144:145]
	ds_read_b128 v[172:175], v224 offset:512
	ds_read_b128 v[180:183], v224 offset:528
	v_or_b32_e32 v144, 32, v142
	v_ashrrev_i32_e32 v145, 31, v144
	v_lshlrev_b64 v[144:145], 5, v[144:145]
	v_lshl_add_u64 v[144:145], s[20:21], 0, v[144:145]
	ds_read_b128 v[184:187], v224 offset:1024
	ds_read_b128 v[188:191], v224 offset:1040
	v_or_b32_e32 v142, 48, v142
	v_ashrrev_i32_e32 v143, 31, v142
	v_lshlrev_b64 v[142:143], 5, v[142:143]
	v_lshl_add_u64 v[142:143], s[20:21], 0, v[142:143]
	ds_read_b128 v[192:195], v224 offset:1536
	ds_read_b128 v[196:199], v224 offset:1552
	s_mov_b64 s[4:5], 0x1000
	v_lshl_add_u64 v[142:143], v[176:177], 0, s[4:5]
	s_movk_i32 s4, 0x1000
	v_add_co_u32_e32 v200, vcc, s4, v176
	s_mov_b32 s4, 0xc0ffd1be
	s_nop 0
	v_addc_co_u32_e32 v201, vcc, 0, v177, vcc
	ds_read_b128 v[208:211], v224 offset:4096
	ds_read_b128 v[212:215], v224 offset:4112
	v_mov_b64_e32 v[240:241], s[4:5]
	s_mov_b64 s[4:5], 0x1200
	s_mov_b32 s10, 0x3fb8aa3b
	v_lshl_add_u64 v[142:143], v[176:177], 0, s[4:5]
	ds_read_b128 v[216:219], v224 offset:4608
	ds_read_b128 v[220:223], v224 offset:4624
	ds_read_b128 v[236:239], v224 offset:5136
	ds_read_b128 v[250:253], v224 offset:5632
	ds_read_b64 v[246:247], v224 offset:5648
	ds_read_b64 v[254:255], v224 offset:5656
	ds_read_b128 v[224:227], v224 offset:5120
	s_mov_b64 s[4:5], 0x1400
	v_cvt_f32_i32_e32 v129, v129
	v_cvt_f32_i32_e32 v128, v128
	v_cvt_f32_i32_e32 v127, v127
	v_cvt_f32_i32_e32 v126, v126
	v_cvt_f32_i32_e32 v121, v121
	v_cvt_f32_i32_e32 v120, v120
	v_cvt_f32_i32_e32 v119, v119
	v_cvt_f32_i32_e32 v118, v118
	v_cvt_f32_i32_e32 v117, v117
	v_cvt_f32_i32_e32 v116, v116
	v_cvt_f32_i32_e32 v115, v115
	v_cvt_f32_i32_e32 v114, v114
	v_cvt_f32_i32_e32 v105, v105
	v_cvt_f32_i32_e32 v104, v104
	v_cvt_f32_i32_e32 v103, v103
	v_cvt_f32_i32_e32 v102, v102
	s_waitcnt lgkmcnt(0)
	v_xor_b32_e32 v133, 0x80000000, v133
	v_xor_b32_e32 v132, 0x80000000, v132
	v_pk_fma_f32 v[146:147], v[130:131], s[10:11], v[240:241] op_sel_hi:[1,0,0] neg_lo:[1,0,0] neg_hi:[1,0,0]
	v_xor_b32_e32 v131, 0x80000000, v141
	v_xor_b32_e32 v130, 0x80000000, v140
	v_pk_fma_f32 v[148:149], v[132:133], s[10:11], v[240:241] op_sel_hi:[1,0,0]
	v_pk_fma_f32 v[144:145], v[130:131], s[10:11], v[240:241] op_sel_hi:[1,0,0]
	v_xor_b32_e32 v131, 0x80000000, v163
	v_xor_b32_e32 v130, 0x80000000, v162
	s_mov_b64 s[4:5], 0x1600
	v_xor_b32_e32 v137, 0x80000000, v137
	v_xor_b32_e32 v136, 0x80000000, v136
	v_pk_fma_f32 v[142:143], v[138:139], s[10:11], v[240:241] op_sel_hi:[1,0,0] neg_lo:[1,0,0] neg_hi:[1,0,0]
	v_pk_fma_f32 v[138:139], v[130:131], s[10:11], v[240:241] op_sel_hi:[1,0,0]
	v_pk_fma_f32 v[150:151], v[134:135], s[10:11], v[240:241] op_sel_hi:[1,0,0] neg_lo:[1,0,0] neg_hi:[1,0,0]
	v_pk_fma_f32 v[152:153], v[136:137], s[10:11], v[240:241] op_sel_hi:[1,0,0]
	v_pk_fma_f32 v[140:141], v[160:161], s[10:11], v[240:241] op_sel_hi:[1,0,0] neg_lo:[1,0,0] neg_hi:[1,0,0]
	v_cvt_f32_i32_e32 v101, v101
	v_cvt_f32_i32_e32 v100, v100
	v_cvt_f32_i32_e32 v99, v99
	v_cvt_f32_i32_e32 v98, v98
	v_cvt_f32_i32_e32 v89, v89
	v_cvt_f32_i32_e32 v88, v88
	v_cvt_f32_i32_e32 v87, v87
	v_cvt_f32_i32_e32 v86, v86
	v_cvt_f32_i32_e32 v85, v85
	v_cvt_f32_i32_e32 v84, v84
	v_cvt_f32_i32_e32 v83, v83
	v_mov_b32_e32 v160, v164
	v_mov_b32_e32 v161, v168
	v_mov_b32_e32 v168, v165
	v_mov_b32_e32 v162, v166
	v_mov_b32_e32 v163, v170
	v_mov_b32_e32 v170, v167
	v_pk_add_f32 v[160:161], v[160:161], v[168:169]
	v_pk_add_f32 v[162:163], v[162:163], v[170:171]
	v_cvt_f32_i32_e32 v167, v111
	v_pk_add_f32 v[160:161], v[160:161], v[162:163]
	v_mov_b32_e32 v162, v174
	v_add_f32_e32 v160, v160, v161
	v_fmamk_f32 v160, v160, 0x3a000000, v1
	v_rsq_f32_e32 v164, v160
	v_mov_b32_e32 v160, v172
	v_mov_b32_e32 v161, v180
	v_mov_b32_e32 v180, v173
	v_mov_b32_e32 v163, v182
	v_mov_b32_e32 v182, v175
	v_pk_add_f32 v[160:161], v[160:161], v[180:181]
	v_pk_add_f32 v[162:163], v[162:163], v[182:183]
	v_cvt_f32_i32_e32 v166, v110
	v_pk_add_f32 v[160:161], v[160:161], v[162:163]
	v_mov_b32_e32 v162, v186
	v_add_f32_e32 v160, v160, v161
	v_fmamk_f32 v160, v160, 0x3a000000, v1
	v_rsq_f32_e32 v172, v160
	v_mov_b32_e32 v160, v184
	v_mov_b32_e32 v161, v188
	v_mov_b32_e32 v188, v185
	v_mov_b32_e32 v163, v190
	v_mov_b32_e32 v190, v187
	v_pk_add_f32 v[160:161], v[160:161], v[188:189]
	v_pk_add_f32 v[162:163], v[162:163], v[190:191]
	v_cvt_f32_i32_e32 v169, v109
	v_pk_add_f32 v[160:161], v[160:161], v[162:163]
	v_mov_b32_e32 v162, v194
	v_add_f32_e32 v160, v160, v161
	v_fmamk_f32 v160, v160, 0x3a000000, v1
	v_rsq_f32_e32 v173, v160
	v_mov_b32_e32 v160, v192
	v_mov_b32_e32 v161, v196
	v_mov_b32_e32 v196, v193
	v_mov_b32_e32 v163, v198
	v_mov_b32_e32 v198, v195
	v_pk_add_f32 v[160:161], v[160:161], v[196:197]
	v_pk_add_f32 v[162:163], v[162:163], v[198:199]
	v_cvt_f32_i32_e32 v168, v108
	v_pk_add_f32 v[160:161], v[160:161], v[162:163]
	v_mov_b32_e32 v162, v210
	v_add_f32_e32 v160, v160, v161
	v_fmamk_f32 v160, v160, 0x3a000000, v1
	v_rsq_f32_e32 v174, v160
	v_mov_b32_e32 v160, v208
	v_mov_b32_e32 v161, v212
	v_mov_b32_e32 v212, v209
	v_mov_b32_e32 v163, v214
	v_mov_b32_e32 v214, v211
	v_pk_add_f32 v[160:161], v[160:161], v[212:213]
	v_pk_add_f32 v[162:163], v[162:163], v[214:215]
	v_cvt_f32_i32_e32 v111, v95
	v_pk_add_f32 v[160:161], v[160:161], v[162:163]
	v_mov_b32_e32 v162, v218
	v_add_f32_e32 v160, v160, v161
	v_fmamk_f32 v160, v160, 0x3a000000, v1
	v_rsq_f32_e32 v175, v160
	v_mov_b32_e32 v160, v216
	v_mov_b32_e32 v161, v220
	v_mov_b32_e32 v220, v217
	v_mov_b32_e32 v163, v222
	v_mov_b32_e32 v222, v219
	v_pk_add_f32 v[160:161], v[160:161], v[220:221]
	v_pk_add_f32 v[162:163], v[162:163], v[222:223]
	v_cvt_f32_i32_e32 v110, v94
	v_pk_add_f32 v[160:161], v[160:161], v[162:163]
	v_cvt_f32_i32_e32 v109, v93
	v_add_f32_e32 v160, v160, v161
	v_cvt_f32_i32_e32 v108, v92
	v_cvt_f32_i32_e32 v95, v79
	v_cvt_f32_i32_e32 v94, v78
	v_cvt_f32_i32_e32 v93, v77
	v_cvt_f32_i32_e32 v92, v76
	v_cvt_f32_i32_e32 v79, v71
	v_cvt_f32_i32_e32 v78, v70
	v_cvt_f32_i32_e32 v77, v69
	v_cvt_f32_i32_e32 v76, v68
	v_cvt_f32_i32_e32 v71, v63
	v_cvt_f32_i32_e32 v70, v62
	v_cvt_f32_i32_e32 v69, v61
	v_cvt_f32_i32_e32 v68, v60
	v_cvt_f32_i32_e32 v63, v47
	v_cvt_f32_i32_e32 v62, v46
	v_cvt_f32_i32_e32 v61, v45
	v_cvt_f32_i32_e32 v60, v44
	v_cvt_f32_i32_e32 v47, v31
	v_cvt_f32_i32_e32 v46, v30
	v_cvt_f32_i32_e32 v45, v29
	v_cvt_f32_i32_e32 v44, v28
	v_cvt_f32_i32_e32 v31, v37
	v_cvt_f32_i32_e32 v30, v36
	v_cvt_f32_i32_e32 v29, v35
	v_cvt_f32_i32_e32 v28, v34
	v_mov_b32_e32 v34, v250
	v_mov_b32_e32 v35, v246
	v_mov_b32_e32 v130, v251
	v_mov_b32_e32 v131, v247
	v_mov_b32_e32 v36, v252
	v_mov_b32_e32 v37, v254
	v_mov_b32_e32 v132, v253
	v_mov_b32_e32 v133, v255
	v_fmamk_f32 v160, v160, 0x3a000000, v1
	v_pk_add_f32 v[34:35], v[34:35], v[130:131]
	v_pk_add_f32 v[36:37], v[36:37], v[132:133]
	v_rsq_f32_e32 v176, v160
	v_mov_b32_e32 v160, v224
	v_mov_b32_e32 v161, v236
	v_mov_b32_e32 v236, v225
	v_mov_b32_e32 v162, v226
	v_mov_b32_e32 v163, v238
	v_mov_b32_e32 v238, v227
	v_pk_add_f32 v[34:35], v[34:35], v[36:37]
	v_pk_add_f32 v[160:161], v[160:161], v[236:237]
	v_pk_add_f32 v[162:163], v[162:163], v[238:239]
	v_cvt_f32_i32_e32 v171, v107
	v_cvt_f32_i32_e32 v107, v91
	v_cvt_f32_i32_e32 v91, v75
	v_cvt_f32_i32_e32 v75, v67
	v_cvt_f32_i32_e32 v67, v59
	v_cvt_f32_i32_e32 v59, v43
	v_cvt_f32_i32_e32 v43, v27
	v_cvt_f32_i32_e32 v27, v25
	v_cvt_f32_i32_e32 v25, v23
	v_add_f32_e32 v23, v34, v35
	v_pk_add_f32 v[160:161], v[160:161], v[162:163]
	v_fmamk_f32 v23, v23, 0x3a000000, v1
	v_add_f32_e32 v160, v160, v161
	v_cvt_f32_i32_e32 v161, v125
	v_mul_f32_e32 v125, v205, v172
	v_rsq_f32_e32 v205, v23
	v_mul_f32_e32 v157, v157, v164
	v_cvt_f32_i32_e32 v170, v106
	v_cvt_f32_i32_e32 v106, v90
	v_cvt_f32_i32_e32 v90, v74
	v_cvt_f32_i32_e32 v74, v66
	v_cvt_f32_i32_e32 v66, v58
	v_cvt_f32_i32_e32 v58, v42
	v_cvt_f32_i32_e32 v42, v26
	v_cvt_f32_i32_e32 v26, v24
	v_cvt_f32_i32_e32 v24, v22
	v_cvt_f32_i32_e32 v23, v21
	v_cvt_f32_i32_e32 v22, v20
	v_pk_mul_f32 v[20:21], v[154:155], v[204:205]
	v_cvt_f32_i32_e32 v165, v113
	v_mul_f32_e32 v34, v20, v157
	v_pk_fma_f32 v[36:37], v[34:35], v[128:129], v[152:153] op_sel_hi:[0,1,1]
	v_exp_f32_e32 v35, v37
	v_cvt_f32_i32_e32 v164, v112
	v_cvt_f32_i32_e32 v113, v97
	v_cvt_f32_i32_e32 v112, v96
	v_cvt_f32_i32_e32 v97, v81
	v_cvt_f32_i32_e32 v96, v80
	v_cvt_f32_i32_e32 v81, v73
	v_cvt_f32_i32_e32 v80, v72
	v_cvt_f32_i32_e32 v73, v65
	v_cvt_f32_i32_e32 v72, v64
	v_cvt_f32_i32_e32 v65, v49
	v_cvt_f32_i32_e32 v64, v48
	v_cvt_f32_i32_e32 v49, v33
	v_cvt_f32_i32_e32 v48, v32
	v_cvt_f32_i32_e32 v33, v39
	v_cvt_f32_i32_e32 v32, v38
	v_pk_fma_f32 v[38:39], v[34:35], v[126:127], v[150:151] op_sel_hi:[0,1,1]
	v_exp_f32_e32 v38, v38
	v_exp_f32_e32 v37, v39
	v_exp_f32_e32 v36, v36
	v_fmamk_f32 v160, v160, 0x3a000000, v1
	v_add_f32_e32 v38, 0x3b808081, v38
	v_add_f32_e32 v35, 0x3b808081, v35
	v_add_f32_e32 v37, 0x3b808081, v37
	v_rcp_f32_e32 v38, v38
	v_rsq_f32_e32 v177, v160
	v_cvt_f32_i32_e32 v160, v124
	v_rcp_f32_e32 v35, v35
	v_rcp_f32_e32 v37, v37
	v_add_f32_e32 v36, 0x3b808081, v36
	v_rcp_f32_e32 v39, v36
	v_cvt_f32_i32_e32 v163, v123
	v_cvt_f32_i32_e32 v162, v122
	v_cvt_pk_u8_f32 v36, v38, 0, 0
	v_cvt_pk_u8_f32 v38, v37, 1, v36
	v_pk_fma_f32 v[36:37], v[34:35], v[160:161], v[148:149] op_sel_hi:[0,1,1]
	v_exp_f32_e32 v37, v37
	v_cvt_pk_u8_f32 v38, v39, 2, v38
	v_cvt_pk_u8_f32 v180, v35, 3, v38
	v_pk_fma_f32 v[38:39], v[34:35], v[162:163], v[146:147] op_sel_hi:[0,1,1]
	v_exp_f32_e32 v38, v38
	v_add_f32_e32 v35, 0x3b808081, v37
	v_exp_f32_e32 v37, v39
	v_exp_f32_e32 v36, v36
	v_add_f32_e32 v38, 0x3b808081, v38
	v_rcp_f32_e32 v38, v38
	v_add_f32_e32 v37, 0x3b808081, v37
	v_rcp_f32_e32 v35, v35
	v_rcp_f32_e32 v37, v37
	v_add_f32_e32 v36, 0x3b808081, v36
	v_rcp_f32_e32 v39, v36
	v_cvt_pk_u8_f32 v36, v38, 0, 0
	v_cvt_pk_u8_f32 v38, v37, 1, v36
	v_pk_fma_f32 v[36:37], v[34:35], v[164:165], v[144:145] op_sel_hi:[0,1,1]
	v_exp_f32_e32 v37, v37
	v_cvt_pk_u8_f32 v38, v39, 2, v38
	v_cvt_pk_u8_f32 v181, v35, 3, v38
	v_pk_fma_f32 v[38:39], v[34:35], v[166:167], v[142:143] op_sel_hi:[0,1,1]
	v_exp_f32_e32 v38, v38
	v_add_f32_e32 v35, 0x3b808081, v37
	v_exp_f32_e32 v37, v39
	v_exp_f32_e32 v36, v36
	v_add_f32_e32 v38, 0x3b808081, v38
	v_rcp_f32_e32 v38, v38
	v_add_f32_e32 v37, 0x3b808081, v37
	v_rcp_f32_e32 v37, v37
	v_add_f32_e32 v36, 0x3b808081, v36
	v_rcp_f32_e32 v39, v36
	v_rcp_f32_e32 v35, v35
	v_cvt_pk_u8_f32 v36, v38, 0, 0
	v_cvt_pk_u8_f32 v38, v37, 1, v36
	v_cvt_pk_u8_f32 v38, v39, 2, v38
	v_pk_fma_f32 v[36:37], v[34:35], v[168:169], v[138:139] op_sel_hi:[0,1,1]
	v_cvt_pk_u8_f32 v182, v35, 3, v38
	v_pk_fma_f32 v[34:35], v[34:35], v[170:171], v[140:141] op_sel_hi:[0,1,1]
	v_exp_f32_e32 v34, v34
	v_exp_f32_e32 v35, v35
	v_exp_f32_e32 v36, v36
	v_exp_f32_e32 v37, v37
	v_add_f32_e32 v34, 0x3b808081, v34
	v_add_f32_e32 v35, 0x3b808081, v35
	v_rcp_f32_e32 v34, v34
	v_rcp_f32_e32 v35, v35
	v_add_f32_e32 v36, 0x3b808081, v36
	v_add_f32_e32 v37, 0x3b808081, v37
	v_rcp_f32_e32 v39, v36
	v_cvt_pk_u8_f32 v34, v34, 0, 0
	v_rcp_f32_e32 v38, v37
	v_cvt_pk_u8_f32 v35, v35, 1, v34
	v_mul_f32_e32 v34, v20, v125
	v_pk_fma_f32 v[36:37], v[34:35], v[120:121], v[152:153] op_sel_hi:[0,1,1]
	v_exp_f32_e32 v37, v37
	v_cvt_pk_u8_f32 v35, v39, 2, v35
	v_cvt_pk_u8_f32 v183, v38, 3, v35
	v_pk_fma_f32 v[38:39], v[34:35], v[118:119], v[150:151] op_sel_hi:[0,1,1]
	v_exp_f32_e32 v38, v38
	v_add_f32_e32 v35, 0x3b808081, v37
	v_exp_f32_e32 v37, v39
	v_exp_f32_e32 v36, v36
	v_add_f32_e32 v38, 0x3b808081, v38
	v_rcp_f32_e32 v38, v38
	v_add_f32_e32 v37, 0x3b808081, v37
	v_rcp_f32_e32 v35, v35
	v_rcp_f32_e32 v37, v37
	v_add_f32_e32 v36, 0x3b808081, v36
	v_rcp_f32_e32 v39, v36
	v_cvt_pk_u8_f32 v36, v38, 0, 0
	v_cvt_pk_u8_f32 v38, v37, 1, v36
	v_pk_fma_f32 v[36:37], v[34:35], v[116:117], v[148:149] op_sel_hi:[0,1,1]
	v_exp_f32_e32 v37, v37
	v_cvt_pk_u8_f32 v38, v39, 2, v38
	v_cvt_pk_u8_f32 v184, v35, 3, v38
	v_pk_fma_f32 v[38:39], v[34:35], v[114:115], v[146:147] op_sel_hi:[0,1,1]
	v_exp_f32_e32 v38, v38
	v_add_f32_e32 v35, 0x3b808081, v37
	v_exp_f32_e32 v37, v39
	v_exp_f32_e32 v36, v36
	v_add_f32_e32 v38, 0x3b808081, v38
	v_rcp_f32_e32 v38, v38
	v_add_f32_e32 v37, 0x3b808081, v37
	v_rcp_f32_e32 v35, v35
	v_rcp_f32_e32 v37, v37
	v_add_f32_e32 v36, 0x3b808081, v36
	v_rcp_f32_e32 v39, v36
	v_cvt_pk_u8_f32 v36, v38, 0, 0
	v_cvt_pk_u8_f32 v38, v37, 1, v36
	v_pk_fma_f32 v[36:37], v[34:35], v[112:113], v[144:145] op_sel_hi:[0,1,1]
	v_exp_f32_e32 v37, v37
	v_cvt_pk_u8_f32 v38, v39, 2, v38
	v_cvt_pk_u8_f32 v185, v35, 3, v38
	v_pk_fma_f32 v[38:39], v[34:35], v[110:111], v[142:143] op_sel_hi:[0,1,1]
	v_exp_f32_e32 v38, v38
	v_add_f32_e32 v35, 0x3b808081, v37
	v_exp_f32_e32 v37, v39
	v_exp_f32_e32 v36, v36
	v_add_f32_e32 v38, 0x3b808081, v38
	v_rcp_f32_e32 v38, v38
	v_add_f32_e32 v37, 0x3b808081, v37
	v_rcp_f32_e32 v37, v37
	v_add_f32_e32 v36, 0x3b808081, v36
	v_rcp_f32_e32 v39, v36
	v_rcp_f32_e32 v35, v35
	v_cvt_pk_u8_f32 v36, v38, 0, 0
	v_cvt_pk_u8_f32 v38, v37, 1, v36
	v_cvt_pk_u8_f32 v38, v39, 2, v38
	v_pk_fma_f32 v[36:37], v[34:35], v[108:109], v[138:139] op_sel_hi:[0,1,1]
	v_cvt_pk_u8_f32 v186, v35, 3, v38
	v_pk_fma_f32 v[34:35], v[34:35], v[106:107], v[140:141] op_sel_hi:[0,1,1]
	v_exp_f32_e32 v34, v34
	v_exp_f32_e32 v35, v35
	v_exp_f32_e32 v36, v36
	v_exp_f32_e32 v37, v37
	v_add_f32_e32 v34, 0x3b808081, v34
	v_add_f32_e32 v35, 0x3b808081, v35
	v_rcp_f32_e32 v34, v34
	v_rcp_f32_e32 v35, v35
	v_add_f32_e32 v36, 0x3b808081, v36
	v_mul_f32_e32 v172, v207, v173
	v_add_f32_e32 v37, 0x3b808081, v37
	v_rcp_f32_e32 v39, v36
	v_cvt_pk_u8_f32 v34, v34, 0, 0
	v_rcp_f32_e32 v38, v37
	v_cvt_pk_u8_f32 v35, v35, 1, v34
	v_mul_f32_e32 v34, v20, v172
	v_pk_fma_f32 v[36:37], v[34:35], v[104:105], v[152:153] op_sel_hi:[0,1,1]
	v_exp_f32_e32 v37, v37
	v_cvt_pk_u8_f32 v35, v39, 2, v35
	v_cvt_pk_u8_f32 v187, v38, 3, v35
	v_pk_fma_f32 v[38:39], v[34:35], v[102:103], v[150:151] op_sel_hi:[0,1,1]
	v_exp_f32_e32 v38, v38
	v_add_f32_e32 v35, 0x3b808081, v37
	v_exp_f32_e32 v37, v39
	v_exp_f32_e32 v36, v36
	v_add_f32_e32 v38, 0x3b808081, v38
	v_rcp_f32_e32 v38, v38
	v_add_f32_e32 v37, 0x3b808081, v37
	v_rcp_f32_e32 v35, v35
	v_rcp_f32_e32 v37, v37
	v_add_f32_e32 v36, 0x3b808081, v36
	v_rcp_f32_e32 v39, v36
	v_cvt_pk_u8_f32 v36, v38, 0, 0
	v_cvt_pk_u8_f32 v38, v37, 1, v36
	v_pk_fma_f32 v[36:37], v[34:35], v[100:101], v[148:149] op_sel_hi:[0,1,1]
	v_exp_f32_e32 v37, v37
	v_cvt_pk_u8_f32 v38, v39, 2, v38
	v_cvt_pk_u8_f32 v188, v35, 3, v38
	v_pk_fma_f32 v[38:39], v[34:35], v[98:99], v[146:147] op_sel_hi:[0,1,1]
	v_exp_f32_e32 v38, v38
	v_add_f32_e32 v35, 0x3b808081, v37
	v_exp_f32_e32 v37, v39
	v_exp_f32_e32 v36, v36
	v_add_f32_e32 v38, 0x3b808081, v38
	v_rcp_f32_e32 v38, v38
	v_add_f32_e32 v37, 0x3b808081, v37
	v_rcp_f32_e32 v35, v35
	v_rcp_f32_e32 v37, v37
	v_add_f32_e32 v36, 0x3b808081, v36
	v_rcp_f32_e32 v39, v36
	v_cvt_pk_u8_f32 v36, v38, 0, 0
	v_cvt_pk_u8_f32 v38, v37, 1, v36
	v_pk_fma_f32 v[36:37], v[34:35], v[96:97], v[144:145] op_sel_hi:[0,1,1]
	v_exp_f32_e32 v37, v37
	v_cvt_pk_u8_f32 v38, v39, 2, v38
	v_cvt_pk_u8_f32 v189, v35, 3, v38
	v_pk_fma_f32 v[38:39], v[34:35], v[94:95], v[142:143] op_sel_hi:[0,1,1]
	v_exp_f32_e32 v38, v38
	v_add_f32_e32 v35, 0x3b808081, v37
	v_exp_f32_e32 v37, v39
	v_exp_f32_e32 v36, v36
	v_add_f32_e32 v38, 0x3b808081, v38
	v_rcp_f32_e32 v38, v38
	v_add_f32_e32 v37, 0x3b808081, v37
	v_rcp_f32_e32 v37, v37
	v_add_f32_e32 v36, 0x3b808081, v36
	v_rcp_f32_e32 v39, v36
	v_rcp_f32_e32 v35, v35
	v_cvt_pk_u8_f32 v36, v38, 0, 0
	v_cvt_pk_u8_f32 v38, v37, 1, v36
	v_cvt_pk_u8_f32 v38, v39, 2, v38
	v_pk_fma_f32 v[36:37], v[34:35], v[92:93], v[138:139] op_sel_hi:[0,1,1]
	v_cvt_pk_u8_f32 v190, v35, 3, v38
	v_pk_fma_f32 v[34:35], v[34:35], v[90:91], v[140:141] op_sel_hi:[0,1,1]
	v_exp_f32_e32 v34, v34
	v_exp_f32_e32 v35, v35
	v_exp_f32_e32 v36, v36
	v_exp_f32_e32 v37, v37
	v_add_f32_e32 v34, 0x3b808081, v34
	v_add_f32_e32 v35, 0x3b808081, v35
	v_rcp_f32_e32 v34, v34
	v_rcp_f32_e32 v35, v35
	v_add_f32_e32 v36, 0x3b808081, v36
	v_mul_f32_e32 v173, v242, v174
	v_add_f32_e32 v37, 0x3b808081, v37
	v_rcp_f32_e32 v39, v36
	v_cvt_pk_u8_f32 v34, v34, 0, 0
	v_rcp_f32_e32 v38, v37
	v_cvt_pk_u8_f32 v35, v35, 1, v34
	v_mul_f32_e32 v34, v20, v173
	v_pk_fma_f32 v[36:37], v[34:35], v[88:89], v[152:153] op_sel_hi:[0,1,1]
	v_exp_f32_e32 v37, v37
	v_cvt_pk_u8_f32 v35, v39, 2, v35
	v_cvt_pk_u8_f32 v191, v38, 3, v35
	v_pk_fma_f32 v[38:39], v[34:35], v[86:87], v[150:151] op_sel_hi:[0,1,1]
	v_exp_f32_e32 v38, v38
	v_add_f32_e32 v35, 0x3b808081, v37
	v_exp_f32_e32 v37, v39
	v_exp_f32_e32 v36, v36
	v_add_f32_e32 v38, 0x3b808081, v38
	v_rcp_f32_e32 v38, v38
	v_add_f32_e32 v37, 0x3b808081, v37
	v_rcp_f32_e32 v35, v35
	v_rcp_f32_e32 v37, v37
	v_add_f32_e32 v36, 0x3b808081, v36
	v_rcp_f32_e32 v39, v36
	v_cvt_f32_i32_e32 v82, v82
	v_cvt_pk_u8_f32 v36, v38, 0, 0
	v_cvt_pk_u8_f32 v38, v37, 1, v36
	v_pk_fma_f32 v[36:37], v[34:35], v[84:85], v[148:149] op_sel_hi:[0,1,1]
	v_exp_f32_e32 v37, v37
	v_cvt_pk_u8_f32 v38, v39, 2, v38
	v_cvt_pk_u8_f32 v192, v35, 3, v38
	v_pk_fma_f32 v[38:39], v[34:35], v[82:83], v[146:147] op_sel_hi:[0,1,1]
	v_exp_f32_e32 v38, v38
	v_add_f32_e32 v35, 0x3b808081, v37
	v_exp_f32_e32 v37, v39
	v_exp_f32_e32 v36, v36
	v_add_f32_e32 v38, 0x3b808081, v38
	v_rcp_f32_e32 v38, v38
	v_add_f32_e32 v37, 0x3b808081, v37
	v_rcp_f32_e32 v35, v35
	v_rcp_f32_e32 v37, v37
	v_add_f32_e32 v36, 0x3b808081, v36
	v_rcp_f32_e32 v39, v36
	v_cvt_pk_u8_f32 v36, v38, 0, 0
	v_cvt_pk_u8_f32 v38, v37, 1, v36
	v_pk_fma_f32 v[36:37], v[34:35], v[80:81], v[144:145] op_sel_hi:[0,1,1]
	v_exp_f32_e32 v37, v37
	v_cvt_pk_u8_f32 v38, v39, 2, v38
	v_cvt_pk_u8_f32 v193, v35, 3, v38
	v_pk_fma_f32 v[38:39], v[34:35], v[78:79], v[142:143] op_sel_hi:[0,1,1]
	v_exp_f32_e32 v38, v38
	v_add_f32_e32 v35, 0x3b808081, v37
	v_exp_f32_e32 v37, v39
	v_exp_f32_e32 v36, v36
	v_add_f32_e32 v38, 0x3b808081, v38
	v_rcp_f32_e32 v38, v38
	v_add_f32_e32 v37, 0x3b808081, v37
	v_rcp_f32_e32 v37, v37
	v_add_f32_e32 v36, 0x3b808081, v36
	v_rcp_f32_e32 v39, v36
	v_rcp_f32_e32 v35, v35
	v_cvt_pk_u8_f32 v36, v38, 0, 0
	v_cvt_pk_u8_f32 v38, v37, 1, v36
	v_cvt_pk_u8_f32 v38, v39, 2, v38
	v_pk_fma_f32 v[36:37], v[34:35], v[76:77], v[138:139] op_sel_hi:[0,1,1]
	v_cvt_pk_u8_f32 v194, v35, 3, v38
	v_pk_fma_f32 v[34:35], v[34:35], v[74:75], v[140:141] op_sel_hi:[0,1,1]
	v_exp_f32_e32 v34, v34
	v_exp_f32_e32 v35, v35
	v_exp_f32_e32 v36, v36
	v_exp_f32_e32 v37, v37
	v_add_f32_e32 v34, 0x3b808081, v34
	v_add_f32_e32 v35, 0x3b808081, v35
	v_rcp_f32_e32 v34, v34
	v_rcp_f32_e32 v35, v35
	v_add_f32_e32 v36, 0x3b808081, v36
	v_mul_f32_e32 v124, v243, v175
	v_add_f32_e32 v37, 0x3b808081, v37
	v_rcp_f32_e32 v39, v36
	v_cvt_pk_u8_f32 v34, v34, 0, 0
	v_rcp_f32_e32 v38, v37
	v_cvt_pk_u8_f32 v35, v35, 1, v34
	v_mul_f32_e32 v34, v20, v124
	v_pk_fma_f32 v[36:37], v[34:35], v[72:73], v[152:153] op_sel_hi:[0,1,1]
	v_exp_f32_e32 v37, v37
	v_cvt_pk_u8_f32 v35, v39, 2, v35
	v_cvt_pk_u8_f32 v195, v38, 3, v35
	v_pk_fma_f32 v[38:39], v[34:35], v[70:71], v[150:151] op_sel_hi:[0,1,1]
	v_exp_f32_e32 v38, v38
	v_add_f32_e32 v35, 0x3b808081, v37
	v_exp_f32_e32 v37, v39
	v_exp_f32_e32 v36, v36
	v_add_f32_e32 v38, 0x3b808081, v38
	v_rcp_f32_e32 v38, v38
	v_add_f32_e32 v37, 0x3b808081, v37
	v_rcp_f32_e32 v35, v35
	v_rcp_f32_e32 v37, v37
	v_add_f32_e32 v36, 0x3b808081, v36
	v_rcp_f32_e32 v39, v36
	v_cvt_pk_u8_f32 v36, v38, 0, 0
	v_cvt_pk_u8_f32 v38, v37, 1, v36
	v_pk_fma_f32 v[36:37], v[34:35], v[68:69], v[148:149] op_sel_hi:[0,1,1]
	v_exp_f32_e32 v37, v37
	v_cvt_pk_u8_f32 v38, v39, 2, v38
	v_cvt_pk_u8_f32 v196, v35, 3, v38
	v_pk_fma_f32 v[38:39], v[34:35], v[66:67], v[146:147] op_sel_hi:[0,1,1]
	v_exp_f32_e32 v38, v38
	v_add_f32_e32 v35, 0x3b808081, v37
	v_exp_f32_e32 v37, v39
	v_exp_f32_e32 v36, v36
	v_add_f32_e32 v38, 0x3b808081, v38
	v_rcp_f32_e32 v38, v38
	v_add_f32_e32 v37, 0x3b808081, v37
	v_rcp_f32_e32 v35, v35
	v_rcp_f32_e32 v37, v37
	v_add_f32_e32 v36, 0x3b808081, v36
	v_rcp_f32_e32 v39, v36
	v_cvt_pk_u8_f32 v36, v38, 0, 0
	v_cvt_pk_u8_f32 v38, v37, 1, v36
	v_pk_fma_f32 v[36:37], v[34:35], v[64:65], v[144:145] op_sel_hi:[0,1,1]
	v_exp_f32_e32 v37, v37
	v_cvt_pk_u8_f32 v38, v39, 2, v38
	v_cvt_pk_u8_f32 v197, v35, 3, v38
	v_pk_fma_f32 v[38:39], v[34:35], v[62:63], v[142:143] op_sel_hi:[0,1,1]
	v_exp_f32_e32 v38, v38
	v_add_f32_e32 v35, 0x3b808081, v37
	v_exp_f32_e32 v37, v39
	v_exp_f32_e32 v36, v36
	v_add_f32_e32 v38, 0x3b808081, v38
	v_rcp_f32_e32 v38, v38
	v_add_f32_e32 v37, 0x3b808081, v37
	v_rcp_f32_e32 v37, v37
	v_add_f32_e32 v36, 0x3b808081, v36
	v_rcp_f32_e32 v39, v36
	v_rcp_f32_e32 v35, v35
	v_cvt_pk_u8_f32 v36, v38, 0, 0
	v_cvt_pk_u8_f32 v38, v37, 1, v36
	v_cvt_pk_u8_f32 v38, v39, 2, v38
	v_pk_fma_f32 v[36:37], v[34:35], v[60:61], v[138:139] op_sel_hi:[0,1,1]
	v_cvt_pk_u8_f32 v198, v35, 3, v38
	v_pk_fma_f32 v[34:35], v[34:35], v[58:59], v[140:141] op_sel_hi:[0,1,1]
	v_exp_f32_e32 v34, v34
	v_exp_f32_e32 v35, v35
	v_exp_f32_e32 v36, v36
	v_exp_f32_e32 v37, v37
	v_add_f32_e32 v34, 0x3b808081, v34
	v_add_f32_e32 v35, 0x3b808081, v35
	v_rcp_f32_e32 v34, v34
	v_rcp_f32_e32 v35, v35
	v_cvt_f32_i32_e32 v57, v57
	v_cvt_f32_i32_e32 v56, v56
	v_add_f32_e32 v36, 0x3b808081, v36
	v_mul_f32_e32 v123, v244, v176
	v_add_f32_e32 v37, 0x3b808081, v37
	v_rcp_f32_e32 v39, v36
	v_cvt_pk_u8_f32 v34, v34, 0, 0
	v_cvt_f32_i32_e32 v55, v55
	v_cvt_f32_i32_e32 v54, v54
	v_rcp_f32_e32 v38, v37
	v_cvt_pk_u8_f32 v35, v35, 1, v34
	v_mul_f32_e32 v34, v20, v123
	v_pk_fma_f32 v[36:37], v[34:35], v[56:57], v[152:153] op_sel_hi:[0,1,1]
	v_exp_f32_e32 v37, v37
	v_cvt_pk_u8_f32 v35, v39, 2, v35
	v_cvt_pk_u8_f32 v199, v38, 3, v35
	v_pk_fma_f32 v[38:39], v[34:35], v[54:55], v[150:151] op_sel_hi:[0,1,1]
	v_exp_f32_e32 v38, v38
	v_add_f32_e32 v35, 0x3b808081, v37
	v_exp_f32_e32 v37, v39
	v_exp_f32_e32 v36, v36
	v_add_f32_e32 v38, 0x3b808081, v38
	v_rcp_f32_e32 v38, v38
	v_add_f32_e32 v37, 0x3b808081, v37
	v_cvt_f32_i32_e32 v53, v53
	v_cvt_f32_i32_e32 v52, v52
	v_rcp_f32_e32 v35, v35
	v_rcp_f32_e32 v37, v37
	v_add_f32_e32 v36, 0x3b808081, v36
	v_rcp_f32_e32 v39, v36
	v_cvt_f32_i32_e32 v51, v51
	v_cvt_f32_i32_e32 v50, v50
	v_cvt_pk_u8_f32 v36, v38, 0, 0
	v_cvt_pk_u8_f32 v38, v37, 1, v36
	v_pk_fma_f32 v[36:37], v[34:35], v[52:53], v[148:149] op_sel_hi:[0,1,1]
	v_exp_f32_e32 v37, v37
	v_cvt_pk_u8_f32 v38, v39, 2, v38
	v_cvt_pk_u8_f32 v200, v35, 3, v38
	v_pk_fma_f32 v[38:39], v[34:35], v[50:51], v[146:147] op_sel_hi:[0,1,1]
	v_exp_f32_e32 v38, v38
	v_add_f32_e32 v35, 0x3b808081, v37
	v_exp_f32_e32 v37, v39
	v_exp_f32_e32 v36, v36
	v_add_f32_e32 v38, 0x3b808081, v38
	v_rcp_f32_e32 v38, v38
	v_add_f32_e32 v37, 0x3b808081, v37
	v_rcp_f32_e32 v35, v35
	v_rcp_f32_e32 v37, v37
	v_add_f32_e32 v36, 0x3b808081, v36
	v_rcp_f32_e32 v39, v36
	v_cvt_pk_u8_f32 v36, v38, 0, 0
	v_cvt_pk_u8_f32 v38, v37, 1, v36
	v_pk_fma_f32 v[36:37], v[34:35], v[48:49], v[144:145] op_sel_hi:[0,1,1]
	v_exp_f32_e32 v37, v37
	v_cvt_pk_u8_f32 v38, v39, 2, v38
	v_cvt_pk_u8_f32 v201, v35, 3, v38
	v_pk_fma_f32 v[38:39], v[34:35], v[46:47], v[142:143] op_sel_hi:[0,1,1]
	v_exp_f32_e32 v38, v38
	v_add_f32_e32 v35, 0x3b808081, v37
	v_exp_f32_e32 v37, v39
	v_exp_f32_e32 v36, v36
	v_add_f32_e32 v38, 0x3b808081, v38
	v_rcp_f32_e32 v38, v38
	v_add_f32_e32 v37, 0x3b808081, v37
	v_rcp_f32_e32 v37, v37
	v_add_f32_e32 v36, 0x3b808081, v36
	v_rcp_f32_e32 v39, v36
	v_rcp_f32_e32 v35, v35
	v_cvt_pk_u8_f32 v36, v38, 0, 0
	v_cvt_pk_u8_f32 v38, v37, 1, v36
	v_cvt_pk_u8_f32 v38, v39, 2, v38
	v_pk_fma_f32 v[36:37], v[34:35], v[44:45], v[138:139] op_sel_hi:[0,1,1]
	v_cvt_pk_u8_f32 v205, v35, 3, v38
	v_pk_fma_f32 v[34:35], v[34:35], v[42:43], v[140:141] op_sel_hi:[0,1,1]
	v_exp_f32_e32 v34, v34
	v_exp_f32_e32 v35, v35
	v_exp_f32_e32 v37, v37
	v_exp_f32_e32 v36, v36
	v_add_f32_e32 v34, 0x3b808081, v34
	v_add_f32_e32 v35, 0x3b808081, v35
	v_rcp_f32_e32 v34, v34
	v_rcp_f32_e32 v35, v35
	v_cvt_f32_i32_e32 v41, v41
	v_cvt_f32_i32_e32 v40, v40
	v_mul_f32_e32 v122, v245, v177
	v_cvt_pk_u8_f32 v34, v34, 0, 0
	v_add_f32_e32 v37, 0x3b808081, v37
	v_add_f32_e32 v36, 0x3b808081, v36
	v_cvt_pk_u8_f32 v35, v35, 1, v34
	v_mul_f32_e32 v34, v20, v122
	v_rcp_f32_e32 v38, v37
	v_rcp_f32_e32 v39, v36
	v_pk_fma_f32 v[36:37], v[34:35], v[40:41], v[152:153] op_sel_hi:[0,1,1]
	v_exp_f32_e32 v37, v37
	v_cvt_f32_i32_e32 v19, v19
	v_cvt_pk_u8_f32 v35, v39, 2, v35
	v_cvt_pk_u8_f32 v207, v38, 3, v35
	v_pk_fma_f32 v[32:33], v[34:35], v[32:33], v[150:151] op_sel_hi:[0,1,1]
	v_add_f32_e32 v35, 0x3b808081, v37
	v_cvt_f32_i32_e32 v18, v18
	v_rcp_f32_e32 v35, v35
	v_cvt_f32_i32_e32 v17, v17
	v_cvt_f32_i32_e32 v16, v16
	v_cvt_f32_i32_e32 v15, v15
	v_pk_fma_f32 v[18:19], v[34:35], v[18:19], v[140:141] op_sel_hi:[0,1,1]
	v_exp_f32_e32 v18, v18
	v_pk_fma_f32 v[22:23], v[34:35], v[22:23], v[138:139] op_sel_hi:[0,1,1]
	v_exp_f32_e32 v19, v19
	v_exp_f32_e32 v22, v22
	v_add_f32_e32 v18, 0x3b808081, v18
	v_rcp_f32_e32 v18, v18
	v_add_f32_e32 v19, 0x3b808081, v19
	v_rcp_f32_e32 v19, v19
	v_add_f32_e32 v22, 0x3b808081, v22
	v_rcp_f32_e32 v22, v22
	v_cvt_f32_i32_e32 v14, v14
	v_cvt_pk_u8_f32 v18, v18, 0, 0
	v_cvt_pk_u8_f32 v19, v19, 1, v18
	v_mul_f32_e32 v18, v20, v21
	v_pk_fma_f32 v[16:17], v[18:19], v[16:17], v[152:153] op_sel_hi:[0,1,1]
	v_cvt_pk_u8_f32 v19, v22, 2, v19
	v_pk_fma_f32 v[14:15], v[18:19], v[14:15], v[150:151] op_sel_hi:[0,1,1]
	v_exp_f32_e32 v14, v14
	v_exp_f32_e32 v15, v15
	v_exp_f32_e32 v16, v16
	v_cvt_f32_i32_e32 v3, v3
	v_add_f32_e32 v14, 0x3b808081, v14
	v_add_f32_e32 v15, 0x3b808081, v15
	v_rcp_f32_e32 v14, v14
	v_rcp_f32_e32 v15, v15
	v_add_f32_e32 v16, 0x3b808081, v16
	v_rcp_f32_e32 v16, v16
	v_cvt_pk_u8_f32 v14, v14, 0, 0
	v_cvt_pk_u8_f32 v14, v15, 1, v14
	v_cvt_f32_i32_e32 v2, v2
	v_cvt_f32_i32_e32 v13, v13
	v_cvt_f32_i32_e32 v12, v12
	v_cvt_pk_u8_f32 v16, v16, 2, v14
	v_cvt_f32_i32_e32 v15, v11
	v_cvt_f32_i32_e32 v14, v10
	v_cvt_f32_i32_e32 v7, v7
	v_cvt_f32_i32_e32 v6, v6
	v_cvt_f32_i32_e32 v5, v5
	v_cvt_f32_i32_e32 v4, v4
	v_cvt_f32_i32_e32 v9, v9
	v_cvt_f32_i32_e32 v8, v8
	v_pk_fma_f32 v[2:3], v[18:19], v[2:3], v[140:141] op_sel_hi:[0,1,1]
	v_pk_fma_f32 v[28:29], v[34:35], v[28:29], v[146:147] op_sel_hi:[0,1,1]
	v_pk_fma_f32 v[24:25], v[34:35], v[24:25], v[142:143] op_sel_hi:[0,1,1]
	v_pk_fma_f32 v[12:13], v[18:19], v[12:13], v[148:149] op_sel_hi:[0,1,1]
	v_pk_fma_f32 v[14:15], v[18:19], v[14:15], v[146:147] op_sel_hi:[0,1,1]
	v_pk_fma_f32 v[6:7], v[18:19], v[6:7], v[142:143] op_sel_hi:[0,1,1]
	v_exp_f32_e32 v2, v2
	v_exp_f32_e32 v32, v32
	v_exp_f32_e32 v28, v28
	v_exp_f32_e32 v24, v24
	v_exp_f32_e32 v11, v13
	v_exp_f32_e32 v13, v14
	v_exp_f32_e32 v6, v6
	v_pk_fma_f32 v[4:5], v[18:19], v[4:5], v[138:139] op_sel_hi:[0,1,1]
	v_exp_f32_e32 v3, v3
	v_exp_f32_e32 v33, v33
	v_pk_fma_f32 v[30:31], v[34:35], v[30:31], v[148:149] op_sel_hi:[0,1,1]
	v_exp_f32_e32 v29, v29
	v_pk_fma_f32 v[26:27], v[34:35], v[26:27], v[144:145] op_sel_hi:[0,1,1]
	v_exp_f32_e32 v25, v25
	v_exp_f32_e32 v14, v15
	v_pk_fma_f32 v[8:9], v[18:19], v[8:9], v[144:145] op_sel_hi:[0,1,1]
	v_exp_f32_e32 v7, v7
	v_exp_f32_e32 v4, v4
	v_exp_f32_e32 v36, v36
	v_exp_f32_e32 v30, v30
	v_exp_f32_e32 v26, v26
	v_exp_f32_e32 v12, v12
	v_exp_f32_e32 v8, v8
	v_exp_f32_e32 v5, v5
	v_exp_f32_e32 v31, v31
	v_exp_f32_e32 v27, v27
	v_exp_f32_e32 v23, v23
	v_exp_f32_e32 v17, v17
	v_exp_f32_e32 v9, v9
	v_add_f32_e32 v2, 0x3b808081, v2
	v_add_f32_e32 v32, 0x3b808081, v32
	v_add_f32_e32 v28, 0x3b808081, v28
	v_add_f32_e32 v24, 0x3b808081, v24
	v_add_f32_e32 v13, 0x3b808081, v13
	v_add_f32_e32 v6, 0x3b808081, v6
	v_add_f32_e32 v3, 0x3b808081, v3
	v_rcp_f32_e32 v2, v2
	v_add_f32_e32 v33, 0x3b808081, v33
	v_rcp_f32_e32 v32, v32
	v_add_f32_e32 v29, 0x3b808081, v29
	v_rcp_f32_e32 v28, v28
	v_add_f32_e32 v25, 0x3b808081, v25
	v_rcp_f32_e32 v24, v24
	v_rcp_f32_e32 v13, v13
	v_add_f32_e32 v14, 0x3b808081, v14
	v_add_f32_e32 v7, 0x3b808081, v7
	v_rcp_f32_e32 v6, v6
	v_add_f32_e32 v4, 0x3b808081, v4
	v_rcp_f32_e32 v3, v3
	v_rcp_f32_e32 v33, v33
	v_add_f32_e32 v36, 0x3b808081, v36
	v_rcp_f32_e32 v29, v29
	v_add_f32_e32 v30, 0x3b808081, v30
	v_rcp_f32_e32 v25, v25
	v_add_f32_e32 v26, 0x3b808081, v26
	v_add_f32_e32 v12, 0x3b808081, v12
	v_rcp_f32_e32 v14, v14
	v_rcp_f32_e32 v7, v7
	v_add_f32_e32 v8, 0x3b808081, v8
	v_add_f32_e32 v5, 0x3b808081, v5
	v_rcp_f32_e32 v4, v4
	v_rcp_f32_e32 v36, v36
	v_add_f32_e32 v31, 0x3b808081, v31
	v_rcp_f32_e32 v30, v30
	v_add_f32_e32 v27, 0x3b808081, v27
	v_rcp_f32_e32 v26, v26
	v_add_f32_e32 v23, 0x3b808081, v23
	v_add_f32_e32 v17, 0x3b808081, v17
	v_add_f32_e32 v11, 0x3b808081, v11
	v_rcp_f32_e32 v12, v12
	v_add_f32_e32 v9, 0x3b808081, v9
	v_rcp_f32_e32 v8, v8
	v_rcp_f32_e32 v5, v5
	v_rcp_f32_e32 v31, v31
	v_rcp_f32_e32 v27, v27
	v_rcp_f32_e32 v23, v23
	v_rcp_f32_e32 v17, v17
	v_rcp_f32_e32 v11, v11
	v_rcp_f32_e32 v9, v9
	v_cvt_pk_u8_f32 v2, v2, 0, 0
	v_cvt_pk_u8_f32 v32, v32, 0, 0
	v_cvt_pk_u8_f32 v28, v28, 0, 0
	v_cvt_pk_u8_f32 v24, v24, 0, 0
	v_cvt_pk_u8_f32 v13, v13, 0, 0
	v_cvt_pk_u8_f32 v6, v6, 0, 0
	v_cvt_pk_u8_f32 v2, v3, 1, v2
	v_cvt_pk_u8_f32 v32, v33, 1, v32
	v_cvt_pk_u8_f32 v28, v29, 1, v28
	v_cvt_pk_u8_f32 v24, v25, 1, v24
	v_cvt_pk_u8_f32 v13, v14, 1, v13
	v_cvt_pk_u8_f32 v6, v7, 1, v6
	v_cvt_pk_u8_f32 v2, v4, 2, v2
	v_cvt_pk_u8_f32 v32, v36, 2, v32
	v_cvt_pk_u8_f32 v28, v30, 2, v28
	v_cvt_pk_u8_f32 v24, v26, 2, v24
	v_cvt_pk_u8_f32 v12, v12, 2, v13
	v_cvt_pk_u8_f32 v6, v8, 2, v6
	v_cvt_pk_u8_f32 v13, v5, 3, v2
	v_lshl_add_u32 v2, v156, 4, 0
	v_cvt_pk_u8_f32 v208, v35, 3, v32
	v_cvt_pk_u8_f32 v209, v31, 3, v28
	v_cvt_pk_u8_f32 v210, v27, 3, v24
	v_cvt_pk_u8_f32 v211, v23, 3, v19
	v_cvt_pk_u8_f32 v10, v17, 3, v16
	v_cvt_pk_u8_f32 v11, v11, 3, v12
	v_cvt_pk_u8_f32 v12, v9, 3, v6
	v_add_u32_e32 v2, 0x24f80, v2
	s_waitcnt vmcnt(0)
	s_barrier
	ds_write_b128 v2, v[10:13]
	s_andn2_b64 vcc, exec, s[40:41]
	s_mov_b64 s[4:5], -1
	s_cbranch_vccnz .LBB0_1002
